# grid barriers: last cross-XCD arriver releases every XCD's workgroups directly (one polling hop less)
# speedup vs baseline: 1.0051x; 1.0051x over previous
.LBB0_796:
	s_or_b64 exec, exec, s[12:13]
	s_and_saveexec_b64 s[6:7], s[14:15]
	s_cbranch_execz .LBB0_798
	global_atomic_add v[0:1], v237, off
	v_cmp_eq_u32_e32 vcc, s10, v0
	s_cbranch_vccz xb_rel_skip_1
	s_sub_u32 s100, s10, 0x1100
	s_subb_u32 s101, s11, 0
	global_atomic_add v17, v237, s[100:101]
	global_atomic_add v17, v237, s[100:101] offset:256
	global_atomic_add v17, v237, s[100:101] offset:512
	global_atomic_add v17, v237, s[100:101] offset:768
	global_atomic_add v17, v237, s[100:101] offset:1024
	global_atomic_add v17, v237, s[100:101] offset:1280
	global_atomic_add v17, v237, s[100:101] offset:1536
	global_atomic_add v17, v237, s[100:101] offset:1792
	global_atomic_add v17, v237, s[100:101] offset:2048
	global_atomic_add v17, v237, s[100:101] offset:2304
	global_atomic_add v17, v237, s[100:101] offset:2560
	global_atomic_add v17, v237, s[100:101] offset:2816
	global_atomic_add v17, v237, s[100:101] offset:3072
	global_atomic_add v17, v237, s[100:101] offset:3328
	global_atomic_add v17, v237, s[100:101] offset:3584
	global_atomic_add v17, v237, s[100:101] offset:3840
xb_rel_skip_1:
.LBB0_798:
	s_or_b64 exec, exec, s[6:7]
	s_mov_b64 s[6:7], exec
	v_mbcnt_lo_u32_b32 v0, s6, 0
	v_mbcnt_hi_u32_b32 v0, s7, v0
	v_cmp_eq_u32_e32 vcc, 0, v0
	s_waitcnt vmcnt(0)
	buffer_inv sc1
	s_and_saveexec_b64 s[10:11], vcc
	s_cbranch_execz .LBB0_800
	s_bcnt1_i32_b64 s6, s[6:7]
	v_mov_b32_e32 v0, s6
	v_mov_b32_e32 v1, 0x2000

.LBB0_903:
	s_or_b64 exec, exec, s[12:13]
	s_and_saveexec_b64 s[6:7], s[14:15]
	s_cbranch_execz .LBB0_905
	global_atomic_add v[0:1], v237, off
	v_cmp_eq_u32_e32 vcc, s10, v0
	s_cbranch_vccz xb_rel_skip_2
	s_sub_u32 s100, s10, 0x1100
	s_subb_u32 s101, s11, 0
	global_atomic_add v17, v237, s[100:101]
	global_atomic_add v17, v237, s[100:101] offset:256
	global_atomic_add v17, v237, s[100:101] offset:512
	global_atomic_add v17, v237, s[100:101] offset:768
	global_atomic_add v17, v237, s[100:101] offset:1024
	global_atomic_add v17, v237, s[100:101] offset:1280
	global_atomic_add v17, v237, s[100:101] offset:1536
	global_atomic_add v17, v237, s[100:101] offset:1792
	global_atomic_add v17, v237, s[100:101] offset:2048
	global_atomic_add v17, v237, s[100:101] offset:2304
	global_atomic_add v17, v237, s[100:101] offset:2560
	global_atomic_add v17, v237, s[100:101] offset:2816
	global_atomic_add v17, v237, s[100:101] offset:3072
	global_atomic_add v17, v237, s[100:101] offset:3328
	global_atomic_add v17, v237, s[100:101] offset:3584
	global_atomic_add v17, v237, s[100:101] offset:3840
xb_rel_skip_2:
.LBB0_905:
	s_or_b64 exec, exec, s[6:7]
	s_mov_b64 s[6:7], exec
	v_mbcnt_lo_u32_b32 v0, s6, 0
	v_mbcnt_hi_u32_b32 v0, s7, v0
	v_cmp_eq_u32_e32 vcc, 0, v0
	s_waitcnt vmcnt(0)
	buffer_inv sc1
	s_and_saveexec_b64 s[10:11], vcc
	s_cbranch_execz .LBB0_907
	s_bcnt1_i32_b64 s6, s[6:7]
	v_mov_b32_e32 v0, s6
	v_mov_b32_e32 v1, 0x2000

.LBB0_1957:
	s_or_b64 exec, exec, s[12:13]
	s_and_saveexec_b64 s[6:7], s[14:15]
	s_cbranch_execz .LBB0_1959
	global_atomic_add v[0:1], v237, off
	v_cmp_eq_u32_e32 vcc, s10, v0
	s_cbranch_vccz xb_rel_skip_3
	s_sub_u32 s100, s10, 0x1100
	s_subb_u32 s101, s11, 0
	global_atomic_add v17, v237, s[100:101]
	global_atomic_add v17, v237, s[100:101] offset:256
	global_atomic_add v17, v237, s[100:101] offset:512
	global_atomic_add v17, v237, s[100:101] offset:768
	global_atomic_add v17, v237, s[100:101] offset:1024
	global_atomic_add v17, v237, s[100:101] offset:1280
	global_atomic_add v17, v237, s[100:101] offset:1536
	global_atomic_add v17, v237, s[100:101] offset:1792
	global_atomic_add v17, v237, s[100:101] offset:2048
	global_atomic_add v17, v237, s[100:101] offset:2304
	global_atomic_add v17, v237, s[100:101] offset:2560
	global_atomic_add v17, v237, s[100:101] offset:2816
	global_atomic_add v17, v237, s[100:101] offset:3072
	global_atomic_add v17, v237, s[100:101] offset:3328
	global_atomic_add v17, v237, s[100:101] offset:3584
	global_atomic_add v17, v237, s[100:101] offset:3840
xb_rel_skip_3:
.LBB0_1959:
	s_or_b64 exec, exec, s[6:7]
	s_mov_b64 s[6:7], exec
	v_mbcnt_lo_u32_b32 v0, s6, 0
	v_mbcnt_hi_u32_b32 v0, s7, v0
	v_cmp_eq_u32_e32 vcc, 0, v0
	s_waitcnt vmcnt(0)
	buffer_inv sc1
	s_and_saveexec_b64 s[10:11], vcc
	s_cbranch_execz .LBB0_1961
	s_bcnt1_i32_b64 s6, s[6:7]
	v_mov_b32_e32 v0, s6
	v_mov_b32_e32 v1, 0x2000

.LBB0_2313:
	s_or_b64 exec, exec, s[14:15]
	s_and_saveexec_b64 s[6:7], s[16:17]
	s_cbranch_execz .LBB0_2315
	global_atomic_add v[0:1], v237, off
	v_cmp_eq_u32_e32 vcc, s12, v0
	s_cbranch_vccz xb_rel_skip_4
	s_sub_u32 s100, s12, 0x1100
	s_subb_u32 s101, s13, 0
	global_atomic_add v17, v237, s[100:101]
	global_atomic_add v17, v237, s[100:101] offset:256
	global_atomic_add v17, v237, s[100:101] offset:512
	global_atomic_add v17, v237, s[100:101] offset:768
	global_atomic_add v17, v237, s[100:101] offset:1024
	global_atomic_add v17, v237, s[100:101] offset:1280
	global_atomic_add v17, v237, s[100:101] offset:1536
	global_atomic_add v17, v237, s[100:101] offset:1792
	global_atomic_add v17, v237, s[100:101] offset:2048
	global_atomic_add v17, v237, s[100:101] offset:2304
	global_atomic_add v17, v237, s[100:101] offset:2560
	global_atomic_add v17, v237, s[100:101] offset:2816
	global_atomic_add v17, v237, s[100:101] offset:3072
	global_atomic_add v17, v237, s[100:101] offset:3328
	global_atomic_add v17, v237, s[100:101] offset:3584
	global_atomic_add v17, v237, s[100:101] offset:3840
xb_rel_skip_4:
.LBB0_2315:
	s_or_b64 exec, exec, s[6:7]
	s_mov_b64 s[6:7], exec
	v_mbcnt_lo_u32_b32 v0, s6, 0
	v_mbcnt_hi_u32_b32 v0, s7, v0
	v_cmp_eq_u32_e32 vcc, 0, v0
	s_waitcnt vmcnt(0)
	buffer_inv sc1
	s_and_saveexec_b64 s[12:13], vcc
	s_cbranch_execz .LBB0_2317
	s_bcnt1_i32_b64 s6, s[6:7]
	v_mov_b32_e32 v0, s6
	v_mov_b32_e32 v1, 0x2000

.LBB0_2475:
	s_or_b64 exec, exec, s[14:15]
	s_and_saveexec_b64 s[6:7], s[16:17]
	s_cbranch_execz .LBB0_2477
	global_atomic_add v[0:1], v237, off
	v_cmp_eq_u32_e32 vcc, s12, v0
	s_cbranch_vccz xb_rel_skip_5
	s_sub_u32 s100, s12, 0x1100
	s_subb_u32 s101, s13, 0
	global_atomic_add v17, v237, s[100:101]
	global_atomic_add v17, v237, s[100:101] offset:256
	global_atomic_add v17, v237, s[100:101] offset:512
	global_atomic_add v17, v237, s[100:101] offset:768
	global_atomic_add v17, v237, s[100:101] offset:1024
	global_atomic_add v17, v237, s[100:101] offset:1280
	global_atomic_add v17, v237, s[100:101] offset:1536
	global_atomic_add v17, v237, s[100:101] offset:1792
	global_atomic_add v17, v237, s[100:101] offset:2048
	global_atomic_add v17, v237, s[100:101] offset:2304
	global_atomic_add v17, v237, s[100:101] offset:2560
	global_atomic_add v17, v237, s[100:101] offset:2816
	global_atomic_add v17, v237, s[100:101] offset:3072
	global_atomic_add v17, v237, s[100:101] offset:3328
	global_atomic_add v17, v237, s[100:101] offset:3584
	global_atomic_add v17, v237, s[100:101] offset:3840
xb_rel_skip_5:
.LBB0_2477:
	s_or_b64 exec, exec, s[6:7]
	s_mov_b64 s[6:7], exec
	v_mbcnt_lo_u32_b32 v0, s6, 0
	v_mbcnt_hi_u32_b32 v0, s7, v0
	v_cmp_eq_u32_e32 vcc, 0, v0
	s_waitcnt vmcnt(0)
	buffer_inv sc1
	s_and_saveexec_b64 s[12:13], vcc
	s_cbranch_execz .LBB0_2479
	s_bcnt1_i32_b64 s6, s[6:7]
	v_mov_b32_e32 v0, s6
	v_mov_b32_e32 v1, 0x2000

.LBB0_2701:
	s_or_b64 exec, exec, s[14:15]
	s_and_saveexec_b64 s[6:7], s[16:17]
	s_cbranch_execz .LBB0_2703
	global_atomic_add v[0:1], v237, off
	v_cmp_eq_u32_e32 vcc, s12, v0
	s_cbranch_vccz xb_rel_skip_6
	s_sub_u32 s100, s12, 0x1100
	s_subb_u32 s101, s13, 0
	global_atomic_add v17, v237, s[100:101]
	global_atomic_add v17, v237, s[100:101] offset:256
	global_atomic_add v17, v237, s[100:101] offset:512
	global_atomic_add v17, v237, s[100:101] offset:768
	global_atomic_add v17, v237, s[100:101] offset:1024
	global_atomic_add v17, v237, s[100:101] offset:1280
	global_atomic_add v17, v237, s[100:101] offset:1536
	global_atomic_add v17, v237, s[100:101] offset:1792
	global_atomic_add v17, v237, s[100:101] offset:2048
	global_atomic_add v17, v237, s[100:101] offset:2304
	global_atomic_add v17, v237, s[100:101] offset:2560
	global_atomic_add v17, v237, s[100:101] offset:2816
	global_atomic_add v17, v237, s[100:101] offset:3072
	global_atomic_add v17, v237, s[100:101] offset:3328
	global_atomic_add v17, v237, s[100:101] offset:3584
	global_atomic_add v17, v237, s[100:101] offset:3840
xb_rel_skip_6:
.LBB0_2703:
	s_or_b64 exec, exec, s[6:7]
	s_mov_b64 s[6:7], exec
	v_mbcnt_lo_u32_b32 v0, s6, 0
	v_mbcnt_hi_u32_b32 v0, s7, v0
	v_cmp_eq_u32_e32 vcc, 0, v0
	s_waitcnt vmcnt(0)
	buffer_inv sc1
	s_and_saveexec_b64 s[12:13], vcc
	s_cbranch_execz .LBB0_2705
	s_bcnt1_i32_b64 s6, s[6:7]
	v_mov_b32_e32 v0, s6
	v_mov_b32_e32 v1, 0x2000
